# final RMSNorm applied from registers after the grid barrier: no intermediate store and re-read of the pre-norm tile
# speedup vs baseline: 1.0080x; 1.0008x over previous
; __device__ __forceinline__ unsigned cvt_pk_bf16(float lo, float hi) { f32x2 v = {lo, hi}; bf16x2_t b = __builtin_convertvector(v, bf16x2_t); return __builtin_bit_cast(unsigned, b); }
;     __device__ __forceinline__ void operator()(const f32x4 (&acc)[2][2][4][2], const Unit& u, int wr, int wc, int fr, int fq) const {
;     ...
;                     for (int n = 0; n < 2; ++n) bs[m][bj][n] = *(const f32x4*)(base + (size_t)(row0 + ai * HALF + m * 16) * DMODEL + col0 + bj * HALF + n * 16);
; #pragma unroll
;             for (int m = 0; m < 4; ++m) { const int row = row0 + ai * HALF + m * 16; const size_t off = (size_t)row * DMODEL + col0; float sq = 0.f;
; #pragma unroll
;                 for (int bj = 0; bj < 2; ++bj)
; #pragma unroll
;                     for (int n = 0; n < 2; ++n) { const size_t o2 = off + bj * HALF + n * 16; const f32x4 o = bs[m][bj][n] + acc[ai][bj][m][n] * alpha;
;                         *(f32x4*)(out + o2) = o; sq += (o[0] * o[0] + o[1] * o[1]) + (o[2] * o[2] + o[3] * o[3]);
;                         if (outb) { u32x2 w; w.x = cvt_pk_bf16(o[0], o[1]); w.y = cvt_pk_bf16(o[2], o[3]); *(u32x2*)(outb + o2) = w; } }
;                 sq += __shfl_xor(sq, 16); sq += __shfl_xor(sq, 32);
;                 if (fq == 0) ssq_out[(size_t)row * 32 + u.pn * 4 + wc] = sq; }
.LBB0_1111:
	v_lshl_or_b32 v188, s0, 8, v208
	v_lshl_add_u32 v192, s12, 8, v206
	v_ashrrev_i32_e32 v189, 31, v188
	v_lshlrev_b64 v[220:221], 2, v[188:189]
	v_ashrrev_i32_e32 v193, 31, v192
	v_lshl_add_u64 v[190:191], s[56:57], 0, v[220:221]
	v_lshlrev_b64 v[234:235], 13, v[192:193]
	v_lshl_add_u64 v[196:197], v[190:191], 0, v[234:235]
	v_add_co_u32_e32 v198, vcc, 0x20000, v196
	v_addc_co_u32_e32 v199, vcc, 0, v197, vcc
	v_add_co_u32_e32 v200, vcc, 0x40000, v196
	v_addc_co_u32_e32 v201, vcc, 0, v197, vcc
	v_add_co_u32_e32 v202, vcc, 0x60000, v196
	v_addc_co_u32_e32 v203, vcc, 0, v197, vcc
	v_add_co_u32_e32 v204, vcc, 0x100000, v196
	v_addc_co_u32_e32 v205, vcc, 0, v197, vcc
	v_add_co_u32_e32 v206, vcc, 0x120000, v196
	v_addc_co_u32_e32 v207, vcc, 0, v197, vcc
	v_add_co_u32_e32 v208, vcc, 0x140000, v196
	v_addc_co_u32_e32 v209, vcc, 0, v197, vcc
	v_add_co_u32_e32 v210, vcc, 0x160000, v196
	v_addc_co_u32_e32 v211, vcc, 0, v197, vcc
	v_lshlrev_b64 v[212:213], 7, v[192:193]
	v_lshl_add_u64 v[212:213], s[18:19], 0, v[212:213]
	s_lshl_b32 s28, s0, 4
	s_lshl_b32 s29, s35, 2
	s_add_i32 s28, s28, s29
	s_mov_b32 s29, 0
	v_lshl_add_u64 v[212:213], s[28:29], 0, v[212:213]
	global_load_dwordx4 v[128:131], v[196:197], off nt
	global_load_dwordx4 v[132:135], v[196:197], off offset:64 nt
	global_load_dwordx4 v[136:139], v[196:197], off offset:512 nt
	global_load_dwordx4 v[140:143], v[196:197], off offset:576 nt
	global_load_dwordx4 v[144:147], v[198:199], off nt
	global_load_dwordx4 v[148:151], v[198:199], off offset:64 nt
	global_load_dwordx4 v[152:155], v[198:199], off offset:512 nt
	global_load_dwordx4 v[156:159], v[198:199], off offset:576 nt
	global_load_dwordx4 v[160:163], v[200:201], off nt
	global_load_dwordx4 v[164:167], v[200:201], off offset:64 nt
	global_load_dwordx4 v[168:171], v[200:201], off offset:512 nt
	global_load_dwordx4 v[172:175], v[200:201], off offset:576 nt
	global_load_dwordx4 v[176:179], v[202:203], off nt
	global_load_dwordx4 v[180:183], v[202:203], off offset:64 nt
	global_load_dwordx4 v[184:187], v[202:203], off offset:512 nt
	global_load_dwordx4 v[188:191], v[202:203], off offset:576 nt
	s_waitcnt vmcnt(12)
	v_pk_fma_f32 v[124:125], v[124:125], 0.5, v[128:129] op_sel_hi:[1,0,1]
	v_pk_fma_f32 v[126:127], v[126:127], 0.5, v[130:131] op_sel_hi:[1,0,1]
	v_pk_fma_f32 v[120:121], v[120:121], 0.5, v[132:133] op_sel_hi:[1,0,1]
	v_pk_fma_f32 v[122:123], v[122:123], 0.5, v[134:135] op_sel_hi:[1,0,1]
	v_pk_fma_f32 v[116:117], v[116:117], 0.5, v[136:137] op_sel_hi:[1,0,1]
	v_pk_fma_f32 v[118:119], v[118:119], 0.5, v[138:139] op_sel_hi:[1,0,1]
	v_pk_fma_f32 v[112:113], v[112:113], 0.5, v[140:141] op_sel_hi:[1,0,1]
	v_pk_fma_f32 v[114:115], v[114:115], 0.5, v[142:143] op_sel_hi:[1,0,1]
	v_mul_f32_e32 v225, v124, v124
	v_mul_f32_e32 v226, v125, v125
	v_fmac_f32_e32 v225, v126, v126
	v_fmac_f32_e32 v226, v127, v127
	v_fmac_f32_e32 v225, v120, v120
	v_fmac_f32_e32 v226, v121, v121
	v_fmac_f32_e32 v225, v122, v122
	v_fmac_f32_e32 v226, v123, v123
	v_fmac_f32_e32 v225, v116, v116
	v_fmac_f32_e32 v226, v117, v117
	v_fmac_f32_e32 v225, v118, v118
	v_fmac_f32_e32 v226, v119, v119
	v_fmac_f32_e32 v225, v112, v112
	v_fmac_f32_e32 v226, v113, v113
	v_fmac_f32_e32 v225, v114, v114
	v_fmac_f32_e32 v226, v115, v115
	v_add_f32_e32 v225, v225, v226
	ds_bpermute_b32 v227, v224, v225
	v_mov_b32_e32 v214, v212
	v_mov_b32_e32 v215, v213
	s_waitcnt lgkmcnt(0)
	v_add_f32_e32 v225, v225, v227
	ds_bpermute_b32 v227, v223, v225
	s_waitcnt lgkmcnt(0)
	v_add_f32_e32 v225, v225, v227
	s_and_saveexec_b64 s[12:13], s[6:7]
	s_cbranch_execz .Lfn_sk0
	global_store_dword v[214:215], v225, off
.Lfn_sk0:
	s_or_b64 exec, exec, s[12:13]
	s_waitcnt vmcnt(8)
	v_pk_fma_f32 v[108:109], v[108:109], 0.5, v[144:145] op_sel_hi:[1,0,1]
	v_pk_fma_f32 v[110:111], v[110:111], 0.5, v[146:147] op_sel_hi:[1,0,1]
	v_pk_fma_f32 v[104:105], v[104:105], 0.5, v[148:149] op_sel_hi:[1,0,1]
	v_pk_fma_f32 v[106:107], v[106:107], 0.5, v[150:151] op_sel_hi:[1,0,1]
	v_pk_fma_f32 v[100:101], v[100:101], 0.5, v[152:153] op_sel_hi:[1,0,1]
	v_pk_fma_f32 v[102:103], v[102:103], 0.5, v[154:155] op_sel_hi:[1,0,1]
	v_pk_fma_f32 v[96:97], v[96:97], 0.5, v[156:157] op_sel_hi:[1,0,1]
	v_pk_fma_f32 v[98:99], v[98:99], 0.5, v[158:159] op_sel_hi:[1,0,1]
	v_mul_f32_e32 v225, v108, v108
	v_mul_f32_e32 v226, v109, v109
	v_fmac_f32_e32 v225, v110, v110
	v_fmac_f32_e32 v226, v111, v111
	v_fmac_f32_e32 v225, v104, v104
	v_fmac_f32_e32 v226, v105, v105
	v_fmac_f32_e32 v225, v106, v106
	v_fmac_f32_e32 v226, v107, v107
	v_fmac_f32_e32 v225, v100, v100
	v_fmac_f32_e32 v226, v101, v101
	v_fmac_f32_e32 v225, v102, v102
	v_fmac_f32_e32 v226, v103, v103
	v_fmac_f32_e32 v225, v96, v96
	v_fmac_f32_e32 v226, v97, v97
	v_fmac_f32_e32 v225, v98, v98
	v_fmac_f32_e32 v226, v99, v99
	v_add_f32_e32 v225, v225, v226
	ds_bpermute_b32 v227, v224, v225
	v_add_co_u32_e32 v214, vcc, 0x800, v212
	v_addc_co_u32_e32 v215, vcc, 0, v213, vcc
	s_waitcnt lgkmcnt(0)
	v_add_f32_e32 v225, v225, v227
	ds_bpermute_b32 v227, v223, v225
	s_waitcnt lgkmcnt(0)
	v_add_f32_e32 v225, v225, v227
	s_and_saveexec_b64 s[12:13], s[6:7]
	s_cbranch_execz .Lfn_sk1
	global_store_dword v[214:215], v225, off
; __device__ __forceinline__ unsigned cvt_pk_bf16(float lo, float hi) { f32x2 v = {lo, hi}; bf16x2_t b = __builtin_convertvector(v, bf16x2_t); return __builtin_bit_cast(unsigned, b); }
;     __device__ __forceinline__ void operator()(const f32x4 (&acc)[2][2][4][2], const Unit& u, int wr, int wc, int fr, int fq) const {
;     ...
;                     for (int n = 0; n < 2; ++n) bs[m][bj][n] = *(const f32x4*)(base + (size_t)(row0 + ai * HALF + m * 16) * DMODEL + col0 + bj * HALF + n * 16);
; #pragma unroll
;             for (int m = 0; m < 4; ++m) { const int row = row0 + ai * HALF + m * 16; const size_t off = (size_t)row * DMODEL + col0; float sq = 0.f;
; #pragma unroll
;                 for (int bj = 0; bj < 2; ++bj)
; #pragma unroll
;                     for (int n = 0; n < 2; ++n) { const size_t o2 = off + bj * HALF + n * 16; const f32x4 o = bs[m][bj][n] + acc[ai][bj][m][n] * alpha;
;                         *(f32x4*)(out + o2) = o; sq += (o[0] * o[0] + o[1] * o[1]) + (o[2] * o[2] + o[3] * o[3]);
;                         if (outb) { u32x2 w; w.x = cvt_pk_bf16(o[0], o[1]); w.y = cvt_pk_bf16(o[2], o[3]); *(u32x2*)(outb + o2) = w; } }
;                 sq += __shfl_xor(sq, 16); sq += __shfl_xor(sq, 32);
;                 if (fq == 0) ssq_out[(size_t)row * 32 + u.pn * 4 + wc] = sq; }
.Lfn_sk1:
	s_or_b64 exec, exec, s[12:13]
	s_waitcnt vmcnt(4)
	v_pk_fma_f32 v[92:93], v[92:93], 0.5, v[160:161] op_sel_hi:[1,0,1]
	v_pk_fma_f32 v[94:95], v[94:95], 0.5, v[162:163] op_sel_hi:[1,0,1]
	v_pk_fma_f32 v[88:89], v[88:89], 0.5, v[164:165] op_sel_hi:[1,0,1]
	v_pk_fma_f32 v[90:91], v[90:91], 0.5, v[166:167] op_sel_hi:[1,0,1]
	v_pk_fma_f32 v[84:85], v[84:85], 0.5, v[168:169] op_sel_hi:[1,0,1]
	v_pk_fma_f32 v[86:87], v[86:87], 0.5, v[170:171] op_sel_hi:[1,0,1]
	v_pk_fma_f32 v[80:81], v[80:81], 0.5, v[172:173] op_sel_hi:[1,0,1]
	v_pk_fma_f32 v[82:83], v[82:83], 0.5, v[174:175] op_sel_hi:[1,0,1]
	v_mul_f32_e32 v225, v92, v92
	v_mul_f32_e32 v226, v93, v93
	v_fmac_f32_e32 v225, v94, v94
	v_fmac_f32_e32 v226, v95, v95
	v_fmac_f32_e32 v225, v88, v88
	v_fmac_f32_e32 v226, v89, v89
	v_fmac_f32_e32 v225, v90, v90
	v_fmac_f32_e32 v226, v91, v91
	v_fmac_f32_e32 v225, v84, v84
	v_fmac_f32_e32 v226, v85, v85
	v_fmac_f32_e32 v225, v86, v86
	v_fmac_f32_e32 v226, v87, v87
	v_fmac_f32_e32 v225, v80, v80
	v_fmac_f32_e32 v226, v81, v81
	v_fmac_f32_e32 v225, v82, v82
	v_fmac_f32_e32 v226, v83, v83
	v_add_f32_e32 v225, v225, v226
	ds_bpermute_b32 v227, v224, v225
	v_add_co_u32_e32 v214, vcc, 0x1000, v212
	v_addc_co_u32_e32 v215, vcc, 0, v213, vcc
	s_waitcnt lgkmcnt(0)
	v_add_f32_e32 v225, v225, v227
	ds_bpermute_b32 v227, v223, v225
	s_waitcnt lgkmcnt(0)
	v_add_f32_e32 v225, v225, v227
	s_and_saveexec_b64 s[12:13], s[6:7]
	s_cbranch_execz .Lfn_sk2
	global_store_dword v[214:215], v225, off
.Lfn_sk2:
	s_or_b64 exec, exec, s[12:13]
	s_waitcnt vmcnt(0)
	v_pk_fma_f32 v[76:77], v[76:77], 0.5, v[176:177] op_sel_hi:[1,0,1]
	v_pk_fma_f32 v[78:79], v[78:79], 0.5, v[178:179] op_sel_hi:[1,0,1]
	v_pk_fma_f32 v[72:73], v[72:73], 0.5, v[180:181] op_sel_hi:[1,0,1]
	v_pk_fma_f32 v[74:75], v[74:75], 0.5, v[182:183] op_sel_hi:[1,0,1]
	v_pk_fma_f32 v[68:69], v[68:69], 0.5, v[184:185] op_sel_hi:[1,0,1]
	v_pk_fma_f32 v[70:71], v[70:71], 0.5, v[186:187] op_sel_hi:[1,0,1]
	v_pk_fma_f32 v[64:65], v[64:65], 0.5, v[188:189] op_sel_hi:[1,0,1]
	v_pk_fma_f32 v[66:67], v[66:67], 0.5, v[190:191] op_sel_hi:[1,0,1]
	v_mul_f32_e32 v225, v76, v76
	v_mul_f32_e32 v226, v77, v77
	v_fmac_f32_e32 v225, v78, v78
	v_fmac_f32_e32 v226, v79, v79
	v_fmac_f32_e32 v225, v72, v72
	v_fmac_f32_e32 v226, v73, v73
	v_fmac_f32_e32 v225, v74, v74
	v_fmac_f32_e32 v226, v75, v75
	v_fmac_f32_e32 v225, v68, v68
	v_fmac_f32_e32 v226, v69, v69
	v_fmac_f32_e32 v225, v70, v70
	v_fmac_f32_e32 v226, v71, v71
	v_fmac_f32_e32 v225, v64, v64
	v_fmac_f32_e32 v226, v65, v65
	v_fmac_f32_e32 v225, v66, v66
	v_fmac_f32_e32 v226, v67, v67
	v_add_f32_e32 v225, v225, v226
	ds_bpermute_b32 v227, v224, v225
	v_add_co_u32_e32 v214, vcc, 0x1800, v212
	v_addc_co_u32_e32 v215, vcc, 0, v213, vcc
	s_waitcnt lgkmcnt(0)
	v_add_f32_e32 v225, v225, v227
	ds_bpermute_b32 v227, v223, v225
	s_waitcnt lgkmcnt(0)
	v_add_f32_e32 v225, v225, v227
	s_and_saveexec_b64 s[12:13], s[6:7]
	s_cbranch_execz .Lfn_sk3
	global_store_dword v[214:215], v225, off
.Lfn_sk3:
	s_or_b64 exec, exec, s[12:13]
	global_load_dwordx4 v[128:131], v[204:205], off nt
	global_load_dwordx4 v[132:135], v[204:205], off offset:64 nt
	global_load_dwordx4 v[136:139], v[204:205], off offset:512 nt
	global_load_dwordx4 v[140:143], v[204:205], off offset:576 nt
	global_load_dwordx4 v[144:147], v[206:207], off nt
	global_load_dwordx4 v[148:151], v[206:207], off offset:64 nt
	global_load_dwordx4 v[152:155], v[206:207], off offset:512 nt
	global_load_dwordx4 v[156:159], v[206:207], off offset:576 nt
	global_load_dwordx4 v[160:163], v[208:209], off nt
	global_load_dwordx4 v[164:167], v[208:209], off offset:64 nt
	global_load_dwordx4 v[168:171], v[208:209], off offset:512 nt
	global_load_dwordx4 v[172:175], v[208:209], off offset:576 nt
	global_load_dwordx4 v[176:179], v[210:211], off nt
	global_load_dwordx4 v[180:183], v[210:211], off offset:64 nt
	global_load_dwordx4 v[184:187], v[210:211], off offset:512 nt
	global_load_dwordx4 v[188:191], v[210:211], off offset:576 nt
	s_waitcnt vmcnt(12)
	v_pk_fma_f32 v[60:61], v[60:61], 0.5, v[128:129] op_sel_hi:[1,0,1]
	v_pk_fma_f32 v[62:63], v[62:63], 0.5, v[130:131] op_sel_hi:[1,0,1]
	v_pk_fma_f32 v[56:57], v[56:57], 0.5, v[132:133] op_sel_hi:[1,0,1]
	v_pk_fma_f32 v[58:59], v[58:59], 0.5, v[134:135] op_sel_hi:[1,0,1]
	v_pk_fma_f32 v[52:53], v[52:53], 0.5, v[136:137] op_sel_hi:[1,0,1]
	v_pk_fma_f32 v[54:55], v[54:55], 0.5, v[138:139] op_sel_hi:[1,0,1]
	v_pk_fma_f32 v[48:49], v[48:49], 0.5, v[140:141] op_sel_hi:[1,0,1]
	v_pk_fma_f32 v[50:51], v[50:51], 0.5, v[142:143] op_sel_hi:[1,0,1]
	v_mul_f32_e32 v225, v60, v60
	v_mul_f32_e32 v226, v61, v61
	v_fmac_f32_e32 v225, v62, v62
	v_fmac_f32_e32 v226, v63, v63
	v_fmac_f32_e32 v225, v56, v56
	v_fmac_f32_e32 v226, v57, v57
	v_fmac_f32_e32 v225, v58, v58
	v_fmac_f32_e32 v226, v59, v59
	v_fmac_f32_e32 v225, v52, v52
	v_fmac_f32_e32 v226, v53, v53
	v_fmac_f32_e32 v225, v54, v54
	v_fmac_f32_e32 v226, v55, v55
	v_fmac_f32_e32 v225, v48, v48
	v_fmac_f32_e32 v226, v49, v49
	v_fmac_f32_e32 v225, v50, v50
	v_fmac_f32_e32 v226, v51, v51
	v_add_f32_e32 v225, v225, v226
	ds_bpermute_b32 v227, v224, v225
	v_add_co_u32_e32 v214, vcc, 0x4000, v212
	v_addc_co_u32_e32 v215, vcc, 0, v213, vcc
	s_waitcnt lgkmcnt(0)
	v_add_f32_e32 v225, v225, v227
	ds_bpermute_b32 v227, v223, v225
	s_waitcnt lgkmcnt(0)
	v_add_f32_e32 v225, v225, v227
	s_and_saveexec_b64 s[12:13], s[6:7]
	s_cbranch_execz .Lfn_sk4
	global_store_dword v[214:215], v225, off
; __device__ __forceinline__ unsigned cvt_pk_bf16(float lo, float hi) { f32x2 v = {lo, hi}; bf16x2_t b = __builtin_convertvector(v, bf16x2_t); return __builtin_bit_cast(unsigned, b); }
;     __device__ __forceinline__ void operator()(const f32x4 (&acc)[2][2][4][2], const Unit& u, int wr, int wc, int fr, int fq) const {
;     ...
;             for (int m = 0; m < 4; ++m) { const int row = row0 + ai * HALF + m * 16; const size_t off = (size_t)row * DMODEL + col0; float sq = 0.f;
; #pragma unroll
;                 for (int bj = 0; bj < 2; ++bj)
; #pragma unroll
;                     for (int n = 0; n < 2; ++n) { const size_t o2 = off + bj * HALF + n * 16; const f32x4 o = bs[m][bj][n] + acc[ai][bj][m][n] * alpha;
;                         *(f32x4*)(out + o2) = o; sq += (o[0] * o[0] + o[1] * o[1]) + (o[2] * o[2] + o[3] * o[3]);
;                         if (outb) { u32x2 w; w.x = cvt_pk_bf16(o[0], o[1]); w.y = cvt_pk_bf16(o[2], o[3]); *(u32x2*)(outb + o2) = w; } }
;                 sq += __shfl_xor(sq, 16); sq += __shfl_xor(sq, 32);
;                 if (fq == 0) ssq_out[(size_t)row * 32 + u.pn * 4 + wc] = sq; }
.Lfn_sk4:
	s_or_b64 exec, exec, s[12:13]
	s_waitcnt vmcnt(8)
	v_pk_fma_f32 v[44:45], v[44:45], 0.5, v[144:145] op_sel_hi:[1,0,1]
	v_pk_fma_f32 v[46:47], v[46:47], 0.5, v[146:147] op_sel_hi:[1,0,1]
	v_pk_fma_f32 v[40:41], v[40:41], 0.5, v[148:149] op_sel_hi:[1,0,1]
	v_pk_fma_f32 v[42:43], v[42:43], 0.5, v[150:151] op_sel_hi:[1,0,1]
	v_pk_fma_f32 v[36:37], v[36:37], 0.5, v[152:153] op_sel_hi:[1,0,1]
	v_pk_fma_f32 v[38:39], v[38:39], 0.5, v[154:155] op_sel_hi:[1,0,1]
	v_pk_fma_f32 v[32:33], v[32:33], 0.5, v[156:157] op_sel_hi:[1,0,1]
	v_pk_fma_f32 v[34:35], v[34:35], 0.5, v[158:159] op_sel_hi:[1,0,1]
	v_mul_f32_e32 v225, v44, v44
	v_mul_f32_e32 v226, v45, v45
	v_fmac_f32_e32 v225, v46, v46
	v_fmac_f32_e32 v226, v47, v47
	v_fmac_f32_e32 v225, v40, v40
	v_fmac_f32_e32 v226, v41, v41
	v_fmac_f32_e32 v225, v42, v42
	v_fmac_f32_e32 v226, v43, v43
	v_fmac_f32_e32 v225, v36, v36
	v_fmac_f32_e32 v226, v37, v37
	v_fmac_f32_e32 v225, v38, v38
	v_fmac_f32_e32 v226, v39, v39
	v_fmac_f32_e32 v225, v32, v32
	v_fmac_f32_e32 v226, v33, v33
	v_fmac_f32_e32 v225, v34, v34
	v_fmac_f32_e32 v226, v35, v35
	v_add_f32_e32 v225, v225, v226
	ds_bpermute_b32 v227, v224, v225
	v_add_co_u32_e32 v214, vcc, 0x4800, v212
	v_addc_co_u32_e32 v215, vcc, 0, v213, vcc
	s_waitcnt lgkmcnt(0)
	v_add_f32_e32 v225, v225, v227
	ds_bpermute_b32 v227, v223, v225
	s_waitcnt lgkmcnt(0)
	v_add_f32_e32 v225, v225, v227
	s_and_saveexec_b64 s[12:13], s[6:7]
	s_cbranch_execz .Lfn_sk5
	global_store_dword v[214:215], v225, off
.Lfn_sk5:
	s_or_b64 exec, exec, s[12:13]
	s_waitcnt vmcnt(4)
	v_pk_fma_f32 v[28:29], v[28:29], 0.5, v[160:161] op_sel_hi:[1,0,1]
	v_pk_fma_f32 v[30:31], v[30:31], 0.5, v[162:163] op_sel_hi:[1,0,1]
	v_pk_fma_f32 v[24:25], v[24:25], 0.5, v[164:165] op_sel_hi:[1,0,1]
	v_pk_fma_f32 v[26:27], v[26:27], 0.5, v[166:167] op_sel_hi:[1,0,1]
	v_pk_fma_f32 v[20:21], v[20:21], 0.5, v[168:169] op_sel_hi:[1,0,1]
	v_pk_fma_f32 v[22:23], v[22:23], 0.5, v[170:171] op_sel_hi:[1,0,1]
	v_pk_fma_f32 v[16:17], v[16:17], 0.5, v[172:173] op_sel_hi:[1,0,1]
	v_pk_fma_f32 v[18:19], v[18:19], 0.5, v[174:175] op_sel_hi:[1,0,1]
	v_mul_f32_e32 v225, v28, v28
	v_mul_f32_e32 v226, v29, v29
	v_fmac_f32_e32 v225, v30, v30
	v_fmac_f32_e32 v226, v31, v31
	v_fmac_f32_e32 v225, v24, v24
	v_fmac_f32_e32 v226, v25, v25
	v_fmac_f32_e32 v225, v26, v26
	v_fmac_f32_e32 v226, v27, v27
	v_fmac_f32_e32 v225, v20, v20
	v_fmac_f32_e32 v226, v21, v21
	v_fmac_f32_e32 v225, v22, v22
	v_fmac_f32_e32 v226, v23, v23
	v_fmac_f32_e32 v225, v16, v16
	v_fmac_f32_e32 v226, v17, v17
	v_fmac_f32_e32 v225, v18, v18
	v_fmac_f32_e32 v226, v19, v19
	v_add_f32_e32 v225, v225, v226
	ds_bpermute_b32 v227, v224, v225
	v_add_co_u32_e32 v214, vcc, 0x5000, v212
	v_addc_co_u32_e32 v215, vcc, 0, v213, vcc
	s_waitcnt lgkmcnt(0)
	v_add_f32_e32 v225, v225, v227
	ds_bpermute_b32 v227, v223, v225
	s_waitcnt lgkmcnt(0)
	v_add_f32_e32 v225, v225, v227
	s_and_saveexec_b64 s[12:13], s[6:7]
	s_cbranch_execz .Lfn_sk6
	global_store_dword v[214:215], v225, off
.Lfn_sk6:
	s_or_b64 exec, exec, s[12:13]
	s_waitcnt vmcnt(0)
	v_pk_fma_f32 v[12:13], v[12:13], 0.5, v[176:177] op_sel_hi:[1,0,1]
	v_pk_fma_f32 v[14:15], v[14:15], 0.5, v[178:179] op_sel_hi:[1,0,1]
	v_pk_fma_f32 v[8:9], v[8:9], 0.5, v[180:181] op_sel_hi:[1,0,1]
	v_pk_fma_f32 v[10:11], v[10:11], 0.5, v[182:183] op_sel_hi:[1,0,1]
	v_pk_fma_f32 v[4:5], v[4:5], 0.5, v[184:185] op_sel_hi:[1,0,1]
	v_pk_fma_f32 v[6:7], v[6:7], 0.5, v[186:187] op_sel_hi:[1,0,1]
	v_pk_fma_f32 v[0:1], v[0:1], 0.5, v[188:189] op_sel_hi:[1,0,1]
	v_pk_fma_f32 v[2:3], v[2:3], 0.5, v[190:191] op_sel_hi:[1,0,1]
	v_mul_f32_e32 v225, v12, v12
	v_mul_f32_e32 v226, v13, v13
	v_fmac_f32_e32 v225, v14, v14
	v_fmac_f32_e32 v226, v15, v15
	v_fmac_f32_e32 v225, v8, v8
	v_fmac_f32_e32 v226, v9, v9
	v_fmac_f32_e32 v225, v10, v10
	v_fmac_f32_e32 v226, v11, v11
	v_fmac_f32_e32 v225, v4, v4
	v_fmac_f32_e32 v226, v5, v5
	v_fmac_f32_e32 v225, v6, v6
	v_fmac_f32_e32 v226, v7, v7
	v_fmac_f32_e32 v225, v0, v0
	v_fmac_f32_e32 v226, v1, v1
	v_fmac_f32_e32 v225, v2, v2
	v_fmac_f32_e32 v226, v3, v3
	v_add_f32_e32 v225, v225, v226
	ds_bpermute_b32 v227, v224, v225
	v_add_co_u32_e32 v214, vcc, 0x5800, v212
	v_addc_co_u32_e32 v215, vcc, 0, v213, vcc
	s_waitcnt lgkmcnt(0)
	v_add_f32_e32 v225, v225, v227
	ds_bpermute_b32 v227, v223, v225
	s_waitcnt lgkmcnt(0)
	v_add_f32_e32 v225, v225, v227
	s_and_saveexec_b64 s[12:13], s[6:7]
	s_cbranch_execz .Lfn_sk7
	global_store_dword v[214:215], v225, off
.Lfn_sk7:
	s_or_b64 exec, exec, s[12:13]
	s_mov_b64 s[12:13], exec

; #define PG8_WAIT_V(n) asm volatile("s_waitcnt vmcnt(" #n ")" ::: "memory")
; #define PG8_BAR __builtin_amdgcn_s_barrier()
; template <class Epi, class Sched, bool ALIGN_EPI = false, bool SP2 = false>
; __device__ __forceinline__ void gemm_phase(PG8_LAS unsigned char* lds, const Gemm g, const Sched& S, const Epi& E) {
;     ...
;     PG8_WAIT_V(0);
;     if constexpr (!ALIGN_EPI) { if (wr == 0) PG8_BAR; }
;     PG8_BAR;
.LBB0_1130:
	s_waitcnt vmcnt(0)
	v_mov_b32_e32 v230, v0
	v_mov_b32_e32 v231, v1
	v_mov_b32_e32 v232, v2
	v_mov_b32_e32 v233, v3
	v_mov_b32_e32 v234, v4
	v_mov_b32_e32 v235, v5
	v_mov_b32_e32 v236, v6
	v_mov_b32_e32 v237, v7
	v_mov_b32_e32 v238, v8
	v_mov_b32_e32 v239, v9
	v_mov_b32_e32 v240, v10
	v_mov_b32_e32 v241, v11
	v_mov_b32_e32 v242, v12
	v_mov_b32_e32 v243, v13
	v_mov_b32_e32 v244, v14
	v_mov_b32_e32 v245, v15
	v_mov_b32_e32 v246, v16
	v_mov_b32_e32 v247, v17
	s_barrier

; __device__ __forceinline__ float row_rstd(const float* ssq, int row) {
;     const f32x4* p = (const f32x4*)(ssq + (size_t)row * 32);
;     float s = 0.f;
; #pragma unroll
;     for (int i = 0; i < 8; ++i) { const f32x4 v = p[i]; s += (v[0] + v[1]) + (v[2] + v[3]); }
;     return __builtin_amdgcn_rsqf(s * (1.0f / DMODEL) + RMS_EPS);
; __global__ void __launch_bounds__(512, 2) mega_fwd(Args a) {
;     ...
;         for (int row = gw; row < M_TOK; row += NGW) {
;             const float rs = row_rstd(SSQ3, row);
;             f32x4* xr = (f32x4*)(XR + (size_t)row * DMODEL) + lane;
;             f32x4 xv[8];
; #pragma unroll
;             for (int j = 0; j < 8; ++j) xv[j] = xr[64 * j];
; #pragma unroll
;             for (int j = 0; j < 8; ++j) xr[64 * j] = xv[j] * rs * gf[64 * j];
.LBB0_1183:
	s_or_b64 exec, exec, s[0:1]
	s_waitcnt lgkmcnt(0)
	v_mov_b32_e32 v0, v222
	s_barrier
	v_mov_b32_e32 v0, v230
	v_mov_b32_e32 v1, v231
	v_mov_b32_e32 v2, v232
	v_mov_b32_e32 v3, v233
	v_mov_b32_e32 v4, v234
	v_mov_b32_e32 v5, v235
	v_mov_b32_e32 v6, v236
	v_mov_b32_e32 v7, v237
	v_mov_b32_e32 v8, v238
	v_mov_b32_e32 v9, v239
	v_mov_b32_e32 v10, v240
	v_mov_b32_e32 v11, v241
	v_mov_b32_e32 v12, v242
	v_mov_b32_e32 v13, v243
	v_mov_b32_e32 v14, v244
	v_mov_b32_e32 v15, v245
	v_mov_b32_e32 v16, v246
	v_mov_b32_e32 v17, v247
	s_add_u32 s98, s58, 0x300000
	s_addc_u32 s99, s59, 0
	v_lshrrev_b32_e32 v248, 4, v222
	v_and_b32_e32 v248, 3, v248
	v_lshlrev_b32_e32 v248, 4, v248
	v_lshl_add_u32 v249, v192, 7, v248
	global_load_dwordx4 v[128:131], v249, s[98:99]
	global_load_dwordx4 v[132:135], v249, s[98:99] offset:64
	s_add_u32 s100, s98, 0x800
	s_addc_u32 s101, s99, 0
	global_load_dwordx4 v[136:139], v249, s[100:101]
	global_load_dwordx4 v[140:143], v249, s[100:101] offset:64
	s_add_u32 s100, s98, 0x1000
	s_addc_u32 s101, s99, 0
	global_load_dwordx4 v[144:147], v249, s[100:101]
	global_load_dwordx4 v[148:151], v249, s[100:101] offset:64
	s_add_u32 s100, s98, 0x1800
	s_addc_u32 s101, s99, 0
	global_load_dwordx4 v[152:155], v249, s[100:101]
	global_load_dwordx4 v[156:159], v249, s[100:101] offset:64
	s_add_u32 s100, s98, 0x4000
	s_addc_u32 s101, s99, 0
	global_load_dwordx4 v[160:163], v249, s[100:101]
	global_load_dwordx4 v[164:167], v249, s[100:101] offset:64
	s_add_u32 s100, s98, 0x4800
	s_addc_u32 s101, s99, 0
	global_load_dwordx4 v[168:171], v249, s[100:101]
	global_load_dwordx4 v[172:175], v249, s[100:101] offset:64
	s_add_u32 s100, s98, 0x5000
	s_addc_u32 s101, s99, 0
	global_load_dwordx4 v[176:179], v249, s[100:101]
	global_load_dwordx4 v[180:183], v249, s[100:101] offset:64
	s_add_u32 s100, s98, 0x5800
	s_addc_u32 s101, s99, 0
	global_load_dwordx4 v[184:187], v249, s[100:101]
	global_load_dwordx4 v[188:191], v249, s[100:101] offset:64
	global_load_dwordx4 v[230:233], v220, s[54:55]
	global_load_dwordx4 v[234:237], v220, s[54:55] offset:64
	global_load_dwordx4 v[238:241], v220, s[54:55] offset:512
	global_load_dwordx4 v[242:245], v220, s[54:55] offset:576
	v_mov_b32_e32 v250, 0x358637bd
	s_waitcnt vmcnt(18)
	v_add_f32_e32 v246, v128, v129
	v_add_f32_e32 v247, v130, v131
	v_add_f32_e32 v251, v132, v133
	v_add_f32_e32 v249, v134, v135
	v_add_f32_e32 v246, v246, v247
	v_add_f32_e32 v251, v251, v249
	v_add_f32_e32 v246, v246, v251
	ds_bpermute_b32 v247, v224, v246
	s_waitcnt lgkmcnt(0)
	v_add_f32_e32 v246, v246, v247
	ds_bpermute_b32 v247, v223, v246
	s_waitcnt lgkmcnt(0)
	v_add_f32_e32 v246, v246, v247
	v_fmamk_f32 v246, v246, 0x3a000000, v250
	v_rsq_f32_e32 v246, v246
	s_waitcnt vmcnt(0)
	s_nop 1
	v_pk_mul_f32 v[124:125], v[246:247], v[124:125] op_sel_hi:[0,1]
	v_pk_mul_f32 v[126:127], v[246:247], v[126:127] op_sel_hi:[0,1]
	v_pk_mul_f32 v[124:125], v[124:125], v[230:231]
	v_pk_mul_f32 v[126:127], v[126:127], v[232:233]
	global_store_dwordx4 v[196:197], v[124:127], off nt
	v_pk_mul_f32 v[120:121], v[246:247], v[120:121] op_sel_hi:[0,1]
	v_pk_mul_f32 v[122:123], v[246:247], v[122:123] op_sel_hi:[0,1]
	v_pk_mul_f32 v[120:121], v[120:121], v[234:235]
	v_pk_mul_f32 v[122:123], v[122:123], v[236:237]
	global_store_dwordx4 v[196:197], v[120:123], off offset:64 nt
	v_pk_mul_f32 v[116:117], v[246:247], v[116:117] op_sel_hi:[0,1]
	v_pk_mul_f32 v[118:119], v[246:247], v[118:119] op_sel_hi:[0,1]
	v_pk_mul_f32 v[116:117], v[116:117], v[238:239]
	v_pk_mul_f32 v[118:119], v[118:119], v[240:241]
	global_store_dwordx4 v[196:197], v[116:119], off offset:512 nt
	v_pk_mul_f32 v[112:113], v[246:247], v[112:113] op_sel_hi:[0,1]
	v_pk_mul_f32 v[114:115], v[246:247], v[114:115] op_sel_hi:[0,1]
	v_pk_mul_f32 v[112:113], v[112:113], v[242:243]
	v_pk_mul_f32 v[114:115], v[114:115], v[244:245]
	global_store_dwordx4 v[196:197], v[112:115], off offset:576 nt
	s_waitcnt vmcnt(16)
	v_add_f32_e32 v246, v136, v137
	v_add_f32_e32 v247, v138, v139
	v_add_f32_e32 v251, v140, v141
	v_add_f32_e32 v249, v142, v143
	v_add_f32_e32 v246, v246, v247
	v_add_f32_e32 v251, v251, v249
	v_add_f32_e32 v246, v246, v251
	ds_bpermute_b32 v247, v224, v246
	s_waitcnt lgkmcnt(0)
	v_add_f32_e32 v246, v246, v247
	ds_bpermute_b32 v247, v223, v246
	s_waitcnt lgkmcnt(0)
	v_add_f32_e32 v246, v246, v247
	v_fmamk_f32 v246, v246, 0x3a000000, v250
	v_rsq_f32_e32 v246, v246
	s_nop 1
	v_pk_mul_f32 v[108:109], v[246:247], v[108:109] op_sel_hi:[0,1]
	v_pk_mul_f32 v[110:111], v[246:247], v[110:111] op_sel_hi:[0,1]
	v_pk_mul_f32 v[108:109], v[108:109], v[230:231]
	v_pk_mul_f32 v[110:111], v[110:111], v[232:233]
	global_store_dwordx4 v[198:199], v[108:111], off nt
	v_pk_mul_f32 v[104:105], v[246:247], v[104:105] op_sel_hi:[0,1]
	v_pk_mul_f32 v[106:107], v[246:247], v[106:107] op_sel_hi:[0,1]
	v_pk_mul_f32 v[104:105], v[104:105], v[234:235]
	v_pk_mul_f32 v[106:107], v[106:107], v[236:237]
	global_store_dwordx4 v[198:199], v[104:107], off offset:64 nt
	v_pk_mul_f32 v[100:101], v[246:247], v[100:101] op_sel_hi:[0,1]
	v_pk_mul_f32 v[102:103], v[246:247], v[102:103] op_sel_hi:[0,1]
	v_pk_mul_f32 v[100:101], v[100:101], v[238:239]
	v_pk_mul_f32 v[102:103], v[102:103], v[240:241]
	global_store_dwordx4 v[198:199], v[100:103], off offset:512 nt
	v_pk_mul_f32 v[96:97], v[246:247], v[96:97] op_sel_hi:[0,1]
	v_pk_mul_f32 v[98:99], v[246:247], v[98:99] op_sel_hi:[0,1]
	v_pk_mul_f32 v[96:97], v[96:97], v[242:243]
	v_pk_mul_f32 v[98:99], v[98:99], v[244:245]
	global_store_dwordx4 v[198:199], v[96:99], off offset:576 nt
	s_waitcnt vmcnt(14)
; __global__ void __launch_bounds__(512, 2) mega_fwd(Args a) {
;     ...
;         for (int row = gw; row < M_TOK; row += NGW) {
;             const float rs = row_rstd(SSQ3, row);
;             f32x4* xr = (f32x4*)(XR + (size_t)row * DMODEL) + lane;
;             f32x4 xv[8];
; #pragma unroll
;             for (int j = 0; j < 8; ++j) xv[j] = xr[64 * j];
; #pragma unroll
;             for (int j = 0; j < 8; ++j) xr[64 * j] = xv[j] * rs * gf[64 * j];
	v_add_f32_e32 v246, v144, v145
	v_add_f32_e32 v247, v146, v147
	v_add_f32_e32 v251, v148, v149
	v_add_f32_e32 v249, v150, v151
	v_add_f32_e32 v246, v246, v247
	v_add_f32_e32 v251, v251, v249
	v_add_f32_e32 v246, v246, v251
	ds_bpermute_b32 v247, v224, v246
	s_waitcnt lgkmcnt(0)
	v_add_f32_e32 v246, v246, v247
	ds_bpermute_b32 v247, v223, v246
	s_waitcnt lgkmcnt(0)
	v_add_f32_e32 v246, v246, v247
	v_fmamk_f32 v246, v246, 0x3a000000, v250
	v_rsq_f32_e32 v246, v246
	s_nop 1
	v_pk_mul_f32 v[92:93], v[246:247], v[92:93] op_sel_hi:[0,1]
	v_pk_mul_f32 v[94:95], v[246:247], v[94:95] op_sel_hi:[0,1]
	v_pk_mul_f32 v[92:93], v[92:93], v[230:231]
	v_pk_mul_f32 v[94:95], v[94:95], v[232:233]
	global_store_dwordx4 v[200:201], v[92:95], off nt
	v_pk_mul_f32 v[88:89], v[246:247], v[88:89] op_sel_hi:[0,1]
	v_pk_mul_f32 v[90:91], v[246:247], v[90:91] op_sel_hi:[0,1]
	v_pk_mul_f32 v[88:89], v[88:89], v[234:235]
	v_pk_mul_f32 v[90:91], v[90:91], v[236:237]
	global_store_dwordx4 v[200:201], v[88:91], off offset:64 nt
	v_pk_mul_f32 v[84:85], v[246:247], v[84:85] op_sel_hi:[0,1]
	v_pk_mul_f32 v[86:87], v[246:247], v[86:87] op_sel_hi:[0,1]
	v_pk_mul_f32 v[84:85], v[84:85], v[238:239]
	v_pk_mul_f32 v[86:87], v[86:87], v[240:241]
	global_store_dwordx4 v[200:201], v[84:87], off offset:512 nt
	v_pk_mul_f32 v[80:81], v[246:247], v[80:81] op_sel_hi:[0,1]
	v_pk_mul_f32 v[82:83], v[246:247], v[82:83] op_sel_hi:[0,1]
	v_pk_mul_f32 v[80:81], v[80:81], v[242:243]
	v_pk_mul_f32 v[82:83], v[82:83], v[244:245]
	global_store_dwordx4 v[200:201], v[80:83], off offset:576 nt
	s_waitcnt vmcnt(12)
	v_add_f32_e32 v246, v152, v153
	v_add_f32_e32 v247, v154, v155
	v_add_f32_e32 v251, v156, v157
	v_add_f32_e32 v249, v158, v159
	v_add_f32_e32 v246, v246, v247
	v_add_f32_e32 v251, v251, v249
	v_add_f32_e32 v246, v246, v251
	ds_bpermute_b32 v247, v224, v246
	s_waitcnt lgkmcnt(0)
	v_add_f32_e32 v246, v246, v247
	ds_bpermute_b32 v247, v223, v246
	s_waitcnt lgkmcnt(0)
	v_add_f32_e32 v246, v246, v247
	v_fmamk_f32 v246, v246, 0x3a000000, v250
	v_rsq_f32_e32 v246, v246
	s_nop 1
	v_pk_mul_f32 v[76:77], v[246:247], v[76:77] op_sel_hi:[0,1]
	v_pk_mul_f32 v[78:79], v[246:247], v[78:79] op_sel_hi:[0,1]
	v_pk_mul_f32 v[76:77], v[76:77], v[230:231]
	v_pk_mul_f32 v[78:79], v[78:79], v[232:233]
	global_store_dwordx4 v[202:203], v[76:79], off nt
	v_pk_mul_f32 v[72:73], v[246:247], v[72:73] op_sel_hi:[0,1]
	v_pk_mul_f32 v[74:75], v[246:247], v[74:75] op_sel_hi:[0,1]
	v_pk_mul_f32 v[72:73], v[72:73], v[234:235]
	v_pk_mul_f32 v[74:75], v[74:75], v[236:237]
	global_store_dwordx4 v[202:203], v[72:75], off offset:64 nt
	v_pk_mul_f32 v[68:69], v[246:247], v[68:69] op_sel_hi:[0,1]
	v_pk_mul_f32 v[70:71], v[246:247], v[70:71] op_sel_hi:[0,1]
	v_pk_mul_f32 v[68:69], v[68:69], v[238:239]
	v_pk_mul_f32 v[70:71], v[70:71], v[240:241]
	global_store_dwordx4 v[202:203], v[68:71], off offset:512 nt
	v_pk_mul_f32 v[64:65], v[246:247], v[64:65] op_sel_hi:[0,1]
	v_pk_mul_f32 v[66:67], v[246:247], v[66:67] op_sel_hi:[0,1]
	v_pk_mul_f32 v[64:65], v[64:65], v[242:243]
	v_pk_mul_f32 v[66:67], v[66:67], v[244:245]
	global_store_dwordx4 v[202:203], v[64:67], off offset:576 nt
	s_waitcnt vmcnt(10)
	v_add_f32_e32 v246, v160, v161
	v_add_f32_e32 v247, v162, v163
	v_add_f32_e32 v251, v164, v165
	v_add_f32_e32 v249, v166, v167
	v_add_f32_e32 v246, v246, v247
	v_add_f32_e32 v251, v251, v249
	v_add_f32_e32 v246, v246, v251
	ds_bpermute_b32 v247, v224, v246
	s_waitcnt lgkmcnt(0)
	v_add_f32_e32 v246, v246, v247
	ds_bpermute_b32 v247, v223, v246
	s_waitcnt lgkmcnt(0)
	v_add_f32_e32 v246, v246, v247
	v_fmamk_f32 v246, v246, 0x3a000000, v250
	v_rsq_f32_e32 v246, v246
	s_nop 1
	v_pk_mul_f32 v[60:61], v[246:247], v[60:61] op_sel_hi:[0,1]
	v_pk_mul_f32 v[62:63], v[246:247], v[62:63] op_sel_hi:[0,1]
	v_pk_mul_f32 v[60:61], v[60:61], v[230:231]
	v_pk_mul_f32 v[62:63], v[62:63], v[232:233]
	global_store_dwordx4 v[204:205], v[60:63], off nt
	v_pk_mul_f32 v[56:57], v[246:247], v[56:57] op_sel_hi:[0,1]
	v_pk_mul_f32 v[58:59], v[246:247], v[58:59] op_sel_hi:[0,1]
	v_pk_mul_f32 v[56:57], v[56:57], v[234:235]
	v_pk_mul_f32 v[58:59], v[58:59], v[236:237]
	global_store_dwordx4 v[204:205], v[56:59], off offset:64 nt
	v_pk_mul_f32 v[52:53], v[246:247], v[52:53] op_sel_hi:[0,1]
	v_pk_mul_f32 v[54:55], v[246:247], v[54:55] op_sel_hi:[0,1]
	v_pk_mul_f32 v[52:53], v[52:53], v[238:239]
	v_pk_mul_f32 v[54:55], v[54:55], v[240:241]
	global_store_dwordx4 v[204:205], v[52:55], off offset:512 nt
	v_pk_mul_f32 v[48:49], v[246:247], v[48:49] op_sel_hi:[0,1]
	v_pk_mul_f32 v[50:51], v[246:247], v[50:51] op_sel_hi:[0,1]
	v_pk_mul_f32 v[48:49], v[48:49], v[242:243]
	v_pk_mul_f32 v[50:51], v[50:51], v[244:245]
	global_store_dwordx4 v[204:205], v[48:51], off offset:576 nt
	s_waitcnt vmcnt(8)
; __global__ void __launch_bounds__(512, 2) mega_fwd(Args a) {
;     ...
;         for (int row = gw; row < M_TOK; row += NGW) {
;             const float rs = row_rstd(SSQ3, row);
;             f32x4* xr = (f32x4*)(XR + (size_t)row * DMODEL) + lane;
;             f32x4 xv[8];
; #pragma unroll
;             for (int j = 0; j < 8; ++j) xv[j] = xr[64 * j];
; #pragma unroll
;             for (int j = 0; j < 8; ++j) xr[64 * j] = xv[j] * rs * gf[64 * j];
	v_add_f32_e32 v246, v168, v169
	v_add_f32_e32 v247, v170, v171
	v_add_f32_e32 v251, v172, v173
	v_add_f32_e32 v249, v174, v175
	v_add_f32_e32 v246, v246, v247
	v_add_f32_e32 v251, v251, v249
	v_add_f32_e32 v246, v246, v251
	ds_bpermute_b32 v247, v224, v246
	s_waitcnt lgkmcnt(0)
	v_add_f32_e32 v246, v246, v247
	ds_bpermute_b32 v247, v223, v246
	s_waitcnt lgkmcnt(0)
	v_add_f32_e32 v246, v246, v247
	v_fmamk_f32 v246, v246, 0x3a000000, v250
	v_rsq_f32_e32 v246, v246
	s_nop 1
	v_pk_mul_f32 v[44:45], v[246:247], v[44:45] op_sel_hi:[0,1]
	v_pk_mul_f32 v[46:47], v[246:247], v[46:47] op_sel_hi:[0,1]
	v_pk_mul_f32 v[44:45], v[44:45], v[230:231]
	v_pk_mul_f32 v[46:47], v[46:47], v[232:233]
	global_store_dwordx4 v[206:207], v[44:47], off nt
	v_pk_mul_f32 v[40:41], v[246:247], v[40:41] op_sel_hi:[0,1]
	v_pk_mul_f32 v[42:43], v[246:247], v[42:43] op_sel_hi:[0,1]
	v_pk_mul_f32 v[40:41], v[40:41], v[234:235]
	v_pk_mul_f32 v[42:43], v[42:43], v[236:237]
	global_store_dwordx4 v[206:207], v[40:43], off offset:64 nt
	v_pk_mul_f32 v[36:37], v[246:247], v[36:37] op_sel_hi:[0,1]
	v_pk_mul_f32 v[38:39], v[246:247], v[38:39] op_sel_hi:[0,1]
	v_pk_mul_f32 v[36:37], v[36:37], v[238:239]
	v_pk_mul_f32 v[38:39], v[38:39], v[240:241]
	global_store_dwordx4 v[206:207], v[36:39], off offset:512 nt
	v_pk_mul_f32 v[32:33], v[246:247], v[32:33] op_sel_hi:[0,1]
	v_pk_mul_f32 v[34:35], v[246:247], v[34:35] op_sel_hi:[0,1]
	v_pk_mul_f32 v[32:33], v[32:33], v[242:243]
	v_pk_mul_f32 v[34:35], v[34:35], v[244:245]
	global_store_dwordx4 v[206:207], v[32:35], off offset:576 nt
	s_waitcnt vmcnt(6)
	v_add_f32_e32 v246, v176, v177
	v_add_f32_e32 v247, v178, v179
	v_add_f32_e32 v251, v180, v181
	v_add_f32_e32 v249, v182, v183
	v_add_f32_e32 v246, v246, v247
	v_add_f32_e32 v251, v251, v249
	v_add_f32_e32 v246, v246, v251
	ds_bpermute_b32 v247, v224, v246
	s_waitcnt lgkmcnt(0)
	v_add_f32_e32 v246, v246, v247
	ds_bpermute_b32 v247, v223, v246
	s_waitcnt lgkmcnt(0)
	v_add_f32_e32 v246, v246, v247
	v_fmamk_f32 v246, v246, 0x3a000000, v250
	v_rsq_f32_e32 v246, v246
	s_nop 1
	v_pk_mul_f32 v[28:29], v[246:247], v[28:29] op_sel_hi:[0,1]
	v_pk_mul_f32 v[30:31], v[246:247], v[30:31] op_sel_hi:[0,1]
	v_pk_mul_f32 v[28:29], v[28:29], v[230:231]
	v_pk_mul_f32 v[30:31], v[30:31], v[232:233]
	global_store_dwordx4 v[208:209], v[28:31], off nt
	v_pk_mul_f32 v[24:25], v[246:247], v[24:25] op_sel_hi:[0,1]
	v_pk_mul_f32 v[26:27], v[246:247], v[26:27] op_sel_hi:[0,1]
	v_pk_mul_f32 v[24:25], v[24:25], v[234:235]
	v_pk_mul_f32 v[26:27], v[26:27], v[236:237]
	global_store_dwordx4 v[208:209], v[24:27], off offset:64 nt
	v_pk_mul_f32 v[20:21], v[246:247], v[20:21] op_sel_hi:[0,1]
	v_pk_mul_f32 v[22:23], v[246:247], v[22:23] op_sel_hi:[0,1]
	v_pk_mul_f32 v[20:21], v[20:21], v[238:239]
	v_pk_mul_f32 v[22:23], v[22:23], v[240:241]
	global_store_dwordx4 v[208:209], v[20:23], off offset:512 nt
	v_pk_mul_f32 v[16:17], v[246:247], v[16:17] op_sel_hi:[0,1]
	v_pk_mul_f32 v[18:19], v[246:247], v[18:19] op_sel_hi:[0,1]
	v_pk_mul_f32 v[16:17], v[16:17], v[242:243]
	v_pk_mul_f32 v[18:19], v[18:19], v[244:245]
	global_store_dwordx4 v[208:209], v[16:19], off offset:576 nt
	s_waitcnt vmcnt(0)
	v_add_f32_e32 v246, v184, v185
	v_add_f32_e32 v247, v186, v187
	v_add_f32_e32 v251, v188, v189
	v_add_f32_e32 v249, v190, v191
	v_add_f32_e32 v246, v246, v247
	v_add_f32_e32 v251, v251, v249
	v_add_f32_e32 v246, v246, v251
	ds_bpermute_b32 v247, v224, v246
	s_waitcnt lgkmcnt(0)
	v_add_f32_e32 v246, v246, v247
	ds_bpermute_b32 v247, v223, v246
	s_waitcnt lgkmcnt(0)
	v_add_f32_e32 v246, v246, v247
	v_fmamk_f32 v246, v246, 0x3a000000, v250
	v_rsq_f32_e32 v246, v246
	s_nop 1
	v_pk_mul_f32 v[12:13], v[246:247], v[12:13] op_sel_hi:[0,1]
	v_pk_mul_f32 v[14:15], v[246:247], v[14:15] op_sel_hi:[0,1]
	v_pk_mul_f32 v[12:13], v[12:13], v[230:231]
	v_pk_mul_f32 v[14:15], v[14:15], v[232:233]
	global_store_dwordx4 v[210:211], v[12:15], off nt
	v_pk_mul_f32 v[8:9], v[246:247], v[8:9] op_sel_hi:[0,1]
	v_pk_mul_f32 v[10:11], v[246:247], v[10:11] op_sel_hi:[0,1]
	v_pk_mul_f32 v[8:9], v[8:9], v[234:235]
	v_pk_mul_f32 v[10:11], v[10:11], v[236:237]
	global_store_dwordx4 v[210:211], v[8:11], off offset:64 nt
	v_pk_mul_f32 v[4:5], v[246:247], v[4:5] op_sel_hi:[0,1]
	v_pk_mul_f32 v[6:7], v[246:247], v[6:7] op_sel_hi:[0,1]
	v_pk_mul_f32 v[4:5], v[4:5], v[238:239]
	v_pk_mul_f32 v[6:7], v[6:7], v[240:241]
	global_store_dwordx4 v[210:211], v[4:7], off offset:512 nt
	v_pk_mul_f32 v[0:1], v[246:247], v[0:1] op_sel_hi:[0,1]
	v_pk_mul_f32 v[2:3], v[246:247], v[2:3] op_sel_hi:[0,1]
	v_pk_mul_f32 v[0:1], v[0:1], v[242:243]
	v_pk_mul_f32 v[2:3], v[2:3], v[244:245]
	global_store_dwordx4 v[210:211], v[0:3], off offset:576 nt
